# baseline (speedup 1.0000x reference)
; __device__ __forceinline__ void ln_phase(const PRef& P, const float* __restrict__ gw, const float* __restrict__ bw, bool write_f32) {
;   float* H = P.out(); bfr* hb = (bfr*)(P.ws() + WS_HB); float2* st = (float2*)(P.ws() + WS_MISC + MS_STATS);
;   const int lane = otid() & 63, wv = obid() * 8 + (otid() >> 6), nw = gridDim.x * 8;
;   for (int row = wv; row < TT; row += 2 * nw) {
;     float4* hp0 = (float4*)(H + (long)row * DM); float4* hp1 = (float4*)(H + (long)(row + nw) * DM); float4 v[2][4]; float s0 = 0.f, s1 = 0.f;
; #pragma unroll
;     for (int i = 0; i < 4; ++i) { v[0][i] = hp0[lane + 64 * i]; v[1][i] = hp1[lane + 64 * i]; }
; #pragma unroll
;     for (int i = 0; i < 4; ++i) { s0 += v[0][i].x + v[0][i].y + v[0][i].z + v[0][i].w; s1 += v[1][i].x + v[1][i].y + v[1][i].z + v[1][i].w; }
; #pragma unroll
;     for (int o = 32; o > 0; o >>= 1) { s0 += __shfl_xor(s0, o); s1 += __shfl_xor(s1, o); }
;     const float mu0 = s0 * (1.f / DM), mu1 = s1 * (1.f / DM); float q0 = 0.f, q1 = 0.f;
; #pragma unroll
;     for (int i = 0; i < 4; ++i) { float a = v[0][i].x - mu0, b = v[0][i].y - mu0, c = v[0][i].z - mu0, d = v[0][i].w - mu0; q0 += a * a + b * b + c * c + d * d;
;       float e = v[1][i].x - mu1, f = v[1][i].y - mu1, g = v[1][i].z - mu1, h = v[1][i].w - mu1; q1 += e * e + f * f + g * g + h * h; }
; #pragma unroll
;     for (int o = 32; o > 0; o >>= 1) { q0 += __shfl_xor(q0, o); q1 += __shfl_xor(q1, o); }
;     const float rs0 = rsqrtf(q0 * (1.f / DM) + 1e-5f), rs1 = rsqrtf(q1 * (1.f / DM) + 1e-5f);
;     if (lane == 0) { st[row] = make_float2(mu0, rs0); st[row + nw] = make_float2(mu1, rs1); }
; #pragma unroll
;     for (int i = 0; i < 4; ++i) { float4 g4 = ((const float4*)gw)[lane + 64 * i], b4 = ((const float4*)bw)[lane + 64 * i]; float4 o4, p4;
;       o4.x = (v[0][i].x - mu0) * rs0 * g4.x + b4.x; o4.y = (v[0][i].y - mu0) * rs0 * g4.y + b4.y; o4.z = (v[0][i].z - mu0) * rs0 * g4.z + b4.z; o4.w = (v[0][i].w - mu0) * rs0 * g4.w + b4.w;
;       p4.x = (v[1][i].x - mu1) * rs1 * g4.x + b4.x; p4.y = (v[1][i].y - mu1) * rs1 * g4.y + b4.y; p4.z = (v[1][i].z - mu1) * rs1 * g4.z + b4.z; p4.w = (v[1][i].w - mu1) * rs1 * g4.w + b4.w;
;       if (write_f32) { hp0[lane + 64 * i] = o4; hp1[lane + 64 * i] = p4; }
;       ((u32x2*)(hb + (long)row * DM))[lane + 64 * i] = u32x2{pk2(o4.x, o4.y), pk2(o4.z, o4.w)};
.LBB0_681:
	v_readlane_b32 s2, v255, 14
	s_cmp_gt_i32 s2, 14
	s_mov_b64 s[8:9], -1
	s_cbranch_scc0 .LBB0_688
	s_mov_b64 s[12:13], exec
	v_readlane_b32 s8, v255, 15
	v_readlane_b32 s9, v255, 16
	s_nop 0
	s_load_dwordx4 s[16:19], s[8:9], 0x10
	s_load_dwordx4 s[20:23], s[8:9], 0xf0
	v_readlane_b32 s2, v255, 13
	v_and_b32_e32 v2, 63, v182
	v_lshrrev_b32_e32 v3, 6, v182
	v_lshlrev_b32_e32 v4, 5, v2
	v_lshlrev_b32_e32 v5, 4, v2
	s_lshl_b32 s10, s2, 12
	s_mov_b32 s14, 0
	v_readfirstlane_b32 s15, v3
	s_lshl_b32 s11, s94, 3
	s_waitcnt lgkmcnt(0)
	s_add_u32 s16, s16, s10
	s_addc_u32 s17, s17, 0
	s_add_u32 s18, s18, s10
	s_addc_u32 s19, s19, 0
	global_load_dwordx4 v[8:11], v4, s[16:17]
	global_load_dwordx4 v[24:27], v4, s[18:19]
	global_load_dwordx4 v[12:15], v4, s[16:17] offset:16
	global_load_dwordx4 v[28:31], v4, s[18:19] offset:16
	global_load_dwordx4 v[16:19], v4, s[16:17] offset:2048
	global_load_dwordx4 v[32:35], v4, s[18:19] offset:2048
	global_load_dwordx4 v[20:23], v4, s[16:17] offset:2064
	global_load_dwordx4 v[36:39], v4, s[18:19] offset:2064
	s_add_u32 s11, s11, s15
	s_lshl_b32 s15, s96, 3
	s_add_u32 s8, s22, 0x3000000
	s_addc_u32 s9, s23, 0
	s_add_u32 s22, s22, 0x1d980000
	s_addc_u32 s23, s23, 0
	s_cmpk_ge_u32 s11, 0x8000
	s_cbranch_scc1 .Llna_done
	s_lshl_b32 s2, s11, 12
	s_add_u32 s16, s20, s2
	s_addc_u32 s17, s21, 0
	s_lshl_b32 s10, s15, 12
	s_add_u32 s18, s16, s10
	s_addc_u32 s19, s17, 0
	global_load_dwordx4 v[40:43], v4, s[16:17]
	global_load_dwordx4 v[44:47], v4, s[16:17] offset:16
	global_load_dwordx4 v[48:51], v4, s[16:17] offset:2048
	global_load_dwordx4 v[52:55], v4, s[16:17] offset:2064
	global_load_dwordx4 v[56:59], v4, s[18:19]
	global_load_dwordx4 v[60:63], v4, s[18:19] offset:16
	global_load_dwordx4 v[64:67], v4, s[18:19] offset:2048
	global_load_dwordx4 v[68:71], v4, s[18:19] offset:2064
	s_lshl_b32 s10, s15, 1
	s_add_u32 s10, s11, s10
	s_cmpk_lt_u32 s10, 0x8000
	s_cselect_b32 s10, s10, s11
	s_lshl_b32 s2, s10, 12
	s_add_u32 s16, s20, s2
	s_addc_u32 s17, s21, 0
	s_lshl_b32 s10, s15, 12
	s_add_u32 s18, s16, s10
	s_addc_u32 s19, s17, 0
	global_load_dwordx4 v[72:75], v4, s[16:17]
	global_load_dwordx4 v[76:79], v4, s[16:17] offset:16
	global_load_dwordx4 v[80:83], v4, s[16:17] offset:2048
	global_load_dwordx4 v[84:87], v4, s[16:17] offset:2064
	global_load_dwordx4 v[88:91], v4, s[18:19]
	global_load_dwordx4 v[92:95], v4, s[18:19] offset:16
	global_load_dwordx4 v[96:99], v4, s[18:19] offset:2048
	global_load_dwordx4 v[100:103], v4, s[18:19] offset:2064
	s_waitcnt vmcnt(8)
	v_add_f32_e32 v104, v40, v41
	v_add_f32_e32 v105, v56, v57
	v_add_f32_e32 v104, v104, v42
	v_add_f32_e32 v105, v105, v58
	v_add_f32_e32 v104, v104, v43
	v_add_f32_e32 v105, v105, v59
	v_add_f32_e32 v104, v104, v44
	v_add_f32_e32 v105, v105, v60
	v_add_f32_e32 v104, v104, v45
	v_add_f32_e32 v105, v105, v61
	v_add_f32_e32 v104, v104, v46
	v_add_f32_e32 v105, v105, v62
	v_add_f32_e32 v104, v104, v47
	v_add_f32_e32 v105, v105, v63
	v_add_f32_e32 v104, v104, v48
	v_add_f32_e32 v105, v105, v64
	v_add_f32_e32 v104, v104, v49
	v_add_f32_e32 v105, v105, v65
	v_add_f32_e32 v104, v104, v50
	v_add_f32_e32 v105, v105, v66
	v_add_f32_e32 v104, v104, v51
	v_add_f32_e32 v105, v105, v67
	v_add_f32_e32 v104, v104, v52
	v_add_f32_e32 v105, v105, v68
	v_add_f32_e32 v104, v104, v53
	v_add_f32_e32 v105, v105, v69
	v_add_f32_e32 v104, v104, v54
	v_add_f32_e32 v105, v105, v70
	v_add_f32_e32 v104, v104, v55
	v_add_f32_e32 v105, v105, v71
	s_nop 1
	v_add_f32_dpp v104, v104, v104 quad_perm:[1,0,3,2] row_mask:0xf bank_mask:0xf
	v_add_f32_dpp v105, v105, v105 quad_perm:[1,0,3,2] row_mask:0xf bank_mask:0xf
	s_nop 1
	v_add_f32_dpp v104, v104, v104 quad_perm:[2,3,0,1] row_mask:0xf bank_mask:0xf
	v_add_f32_dpp v105, v105, v105 quad_perm:[2,3,0,1] row_mask:0xf bank_mask:0xf
	s_nop 1
	v_add_f32_dpp v104, v104, v104 row_half_mirror row_mask:0xf bank_mask:0xf
	v_add_f32_dpp v105, v105, v105 row_half_mirror row_mask:0xf bank_mask:0xf
	s_nop 1
	v_add_f32_dpp v104, v104, v104 row_mirror row_mask:0xf bank_mask:0xf
	v_add_f32_dpp v105, v105, v105 row_mirror row_mask:0xf bank_mask:0xf
	s_nop 1
	v_readlane_b32 s2, v104, 0
	v_readlane_b32 s10, v104, 16
	v_readlane_b32 s16, v104, 32
	v_readlane_b32 s17, v104, 48
	v_readlane_b32 s18, v105, 0
	v_readlane_b32 s19, v105, 16
	v_mov_b32_e32 v104, s2
	v_add_f32_e32 v104, s10, v104
	v_add_f32_e32 v104, s16, v104
	v_add_f32_e32 v104, s17, v104
	v_readlane_b32 s2, v105, 32
	v_readlane_b32 s10, v105, 48
	v_mov_b32_e32 v105, s18
	v_add_f32_e32 v105, s19, v105
	s_nop 0
	v_add_f32_e32 v105, s2, v105
	v_add_f32_e32 v105, s10, v105
	v_mul_f32_e32 v108, 0x3a800000, v104
	v_mul_f32_e32 v110, 0x3a800000, v105
	v_sub_f32_e32 v40, v40, v108
	v_sub_f32_e32 v56, v56, v110
	v_sub_f32_e32 v41, v41, v108
	v_sub_f32_e32 v57, v57, v110
	v_sub_f32_e32 v42, v42, v108
	v_sub_f32_e32 v58, v58, v110
	v_sub_f32_e32 v43, v43, v108
	v_sub_f32_e32 v59, v59, v110
	v_sub_f32_e32 v44, v44, v108
	v_sub_f32_e32 v60, v60, v110
	v_sub_f32_e32 v45, v45, v108
	v_sub_f32_e32 v61, v61, v110
	v_sub_f32_e32 v46, v46, v108
	v_sub_f32_e32 v62, v62, v110
	v_sub_f32_e32 v47, v47, v108
	v_sub_f32_e32 v63, v63, v110
	v_sub_f32_e32 v48, v48, v108
	v_sub_f32_e32 v64, v64, v110
	v_sub_f32_e32 v49, v49, v108
	v_sub_f32_e32 v65, v65, v110
	v_sub_f32_e32 v50, v50, v108
	v_sub_f32_e32 v66, v66, v110
	v_sub_f32_e32 v51, v51, v108
	v_sub_f32_e32 v67, v67, v110
	v_sub_f32_e32 v52, v52, v108
	v_sub_f32_e32 v68, v68, v110
	v_sub_f32_e32 v53, v53, v108
	v_sub_f32_e32 v69, v69, v110
	v_sub_f32_e32 v54, v54, v108
	v_sub_f32_e32 v70, v70, v110
	v_sub_f32_e32 v55, v55, v108
	v_sub_f32_e32 v71, v71, v110
; __device__ __forceinline__ void ln_phase(const PRef& P, const float* __restrict__ gw, const float* __restrict__ bw, bool write_f32) {
;   float* H = P.out(); bfr* hb = (bfr*)(P.ws() + WS_HB); float2* st = (float2*)(P.ws() + WS_MISC + MS_STATS);
;   const int lane = otid() & 63, wv = obid() * 8 + (otid() >> 6), nw = gridDim.x * 8;
;   for (int row = wv; row < TT; row += 2 * nw) {
;     float4* hp0 = (float4*)(H + (long)row * DM); float4* hp1 = (float4*)(H + (long)(row + nw) * DM); float4 v[2][4]; float s0 = 0.f, s1 = 0.f;
; #pragma unroll
;     for (int i = 0; i < 4; ++i) { v[0][i] = hp0[lane + 64 * i]; v[1][i] = hp1[lane + 64 * i]; }
; #pragma unroll
;     for (int i = 0; i < 4; ++i) { s0 += v[0][i].x + v[0][i].y + v[0][i].z + v[0][i].w; s1 += v[1][i].x + v[1][i].y + v[1][i].z + v[1][i].w; }
; #pragma unroll
;     for (int o = 32; o > 0; o >>= 1) { s0 += __shfl_xor(s0, o); s1 += __shfl_xor(s1, o); }
;     const float mu0 = s0 * (1.f / DM), mu1 = s1 * (1.f / DM); float q0 = 0.f, q1 = 0.f;
; #pragma unroll
;     for (int i = 0; i < 4; ++i) { float a = v[0][i].x - mu0, b = v[0][i].y - mu0, c = v[0][i].z - mu0, d = v[0][i].w - mu0; q0 += a * a + b * b + c * c + d * d;
;       float e = v[1][i].x - mu1, f = v[1][i].y - mu1, g = v[1][i].z - mu1, h = v[1][i].w - mu1; q1 += e * e + f * f + g * g + h * h; }
; #pragma unroll
;     for (int o = 32; o > 0; o >>= 1) { q0 += __shfl_xor(q0, o); q1 += __shfl_xor(q1, o); }
;     const float rs0 = rsqrtf(q0 * (1.f / DM) + 1e-5f), rs1 = rsqrtf(q1 * (1.f / DM) + 1e-5f);
;     if (lane == 0) { st[row] = make_float2(mu0, rs0); st[row + nw] = make_float2(mu1, rs1); }
; #pragma unroll
;     for (int i = 0; i < 4; ++i) { float4 g4 = ((const float4*)gw)[lane + 64 * i], b4 = ((const float4*)bw)[lane + 64 * i]; float4 o4, p4;
;       o4.x = (v[0][i].x - mu0) * rs0 * g4.x + b4.x; o4.y = (v[0][i].y - mu0) * rs0 * g4.y + b4.y; o4.z = (v[0][i].z - mu0) * rs0 * g4.z + b4.z; o4.w = (v[0][i].w - mu0) * rs0 * g4.w + b4.w;
;       p4.x = (v[1][i].x - mu1) * rs1 * g4.x + b4.x; p4.y = (v[1][i].y - mu1) * rs1 * g4.y + b4.y; p4.z = (v[1][i].z - mu1) * rs1 * g4.z + b4.z; p4.w = (v[1][i].w - mu1) * rs1 * g4.w + b4.w;
;       if (write_f32) { hp0[lane + 64 * i] = o4; hp1[lane + 64 * i] = p4; }
;       ((u32x2*)(hb + (long)row * DM))[lane + 64 * i] = u32x2{pk2(o4.x, o4.y), pk2(o4.z, o4.w)};
	v_mul_f32_e32 v106, v40, v40
	v_mul_f32_e32 v107, v56, v56
	v_fmac_f32_e32 v106, v41, v41
	v_fmac_f32_e32 v107, v57, v57
	v_fmac_f32_e32 v106, v42, v42
	v_fmac_f32_e32 v107, v58, v58
	v_fmac_f32_e32 v106, v43, v43
	v_fmac_f32_e32 v107, v59, v59
	v_fmac_f32_e32 v106, v44, v44
	v_fmac_f32_e32 v107, v60, v60
	v_fmac_f32_e32 v106, v45, v45
	v_fmac_f32_e32 v107, v61, v61
	v_fmac_f32_e32 v106, v46, v46
	v_fmac_f32_e32 v107, v62, v62
	v_fmac_f32_e32 v106, v47, v47
	v_fmac_f32_e32 v107, v63, v63
	v_fmac_f32_e32 v106, v48, v48
	v_fmac_f32_e32 v107, v64, v64
	v_fmac_f32_e32 v106, v49, v49
	v_fmac_f32_e32 v107, v65, v65
	v_fmac_f32_e32 v106, v50, v50
	v_fmac_f32_e32 v107, v66, v66
	v_fmac_f32_e32 v106, v51, v51
	v_fmac_f32_e32 v107, v67, v67
	v_fmac_f32_e32 v106, v52, v52
	v_fmac_f32_e32 v107, v68, v68
	v_fmac_f32_e32 v106, v53, v53
	v_fmac_f32_e32 v107, v69, v69
	v_fmac_f32_e32 v106, v54, v54
	v_fmac_f32_e32 v107, v70, v70
	v_fmac_f32_e32 v106, v55, v55
	v_fmac_f32_e32 v107, v71, v71
	s_nop 1
	v_add_f32_dpp v106, v106, v106 quad_perm:[1,0,3,2] row_mask:0xf bank_mask:0xf
	v_add_f32_dpp v107, v107, v107 quad_perm:[1,0,3,2] row_mask:0xf bank_mask:0xf
	s_nop 1
	v_add_f32_dpp v106, v106, v106 quad_perm:[2,3,0,1] row_mask:0xf bank_mask:0xf
	v_add_f32_dpp v107, v107, v107 quad_perm:[2,3,0,1] row_mask:0xf bank_mask:0xf
	s_nop 1
	v_add_f32_dpp v106, v106, v106 row_half_mirror row_mask:0xf bank_mask:0xf
	v_add_f32_dpp v107, v107, v107 row_half_mirror row_mask:0xf bank_mask:0xf
	s_nop 1
	v_add_f32_dpp v106, v106, v106 row_mirror row_mask:0xf bank_mask:0xf
	v_add_f32_dpp v107, v107, v107 row_mirror row_mask:0xf bank_mask:0xf
	s_nop 1
	v_readlane_b32 s2, v106, 0
	v_readlane_b32 s10, v106, 16
	v_readlane_b32 s16, v106, 32
	v_readlane_b32 s17, v106, 48
	v_readlane_b32 s18, v107, 0
	v_readlane_b32 s19, v107, 16
	v_mov_b32_e32 v106, s2
	v_add_f32_e32 v106, s10, v106
	v_add_f32_e32 v106, s16, v106
	v_add_f32_e32 v106, s17, v106
	v_readlane_b32 s2, v107, 32
	v_readlane_b32 s10, v107, 48
	v_mov_b32_e32 v107, s18
	v_add_f32_e32 v107, s19, v107
	s_nop 0
	v_add_f32_e32 v107, s2, v107
	v_add_f32_e32 v107, s10, v107
	v_mul_f32_e32 v106, 0x3a800000, v106
	v_mul_f32_e32 v107, 0x3a800000, v107
	v_add_f32_e32 v106, 0x3727c5ac, v106
	v_add_f32_e32 v107, 0x3727c5ac, v107
	v_rsq_f32_e32 v109, v106
	v_rsq_f32_e32 v111, v107
	s_nop 0
	v_mul_f32_e32 v40, v40, v109
	v_mul_f32_e32 v56, v56, v111
	v_mul_f32_e32 v41, v41, v109
	v_mul_f32_e32 v57, v57, v111
	v_mul_f32_e32 v42, v42, v109
	v_mul_f32_e32 v58, v58, v111
	v_mul_f32_e32 v43, v43, v109
	v_mul_f32_e32 v59, v59, v111
	v_mul_f32_e32 v44, v44, v109
	v_mul_f32_e32 v60, v60, v111
	v_mul_f32_e32 v45, v45, v109
	v_mul_f32_e32 v61, v61, v111
	v_mul_f32_e32 v46, v46, v109
	v_mul_f32_e32 v62, v62, v111
	v_mul_f32_e32 v47, v47, v109
	v_mul_f32_e32 v63, v63, v111
	v_mul_f32_e32 v48, v48, v109
	v_mul_f32_e32 v64, v64, v111
	v_mul_f32_e32 v49, v49, v109
	v_mul_f32_e32 v65, v65, v111
	v_mul_f32_e32 v50, v50, v109
	v_mul_f32_e32 v66, v66, v111
	v_mul_f32_e32 v51, v51, v109
	v_mul_f32_e32 v67, v67, v111
	v_mul_f32_e32 v52, v52, v109
	v_mul_f32_e32 v68, v68, v111
	v_mul_f32_e32 v53, v53, v109
	v_mul_f32_e32 v69, v69, v111
	v_mul_f32_e32 v54, v54, v109
	v_mul_f32_e32 v70, v70, v111
	v_mul_f32_e32 v55, v55, v109
	v_mul_f32_e32 v71, v71, v111
	v_fma_f32 v40, v40, v8, v24
	v_fma_f32 v56, v56, v8, v24
	v_fma_f32 v41, v41, v9, v25
	v_fma_f32 v57, v57, v9, v25
	v_fma_f32 v42, v42, v10, v26
	v_fma_f32 v58, v58, v10, v26
	v_fma_f32 v43, v43, v11, v27
	v_fma_f32 v59, v59, v11, v27
	v_fma_f32 v44, v44, v12, v28
	v_fma_f32 v60, v60, v12, v28
	v_fma_f32 v45, v45, v13, v29
	v_fma_f32 v61, v61, v13, v29
	v_fma_f32 v46, v46, v14, v30
	v_fma_f32 v62, v62, v14, v30
	v_fma_f32 v47, v47, v15, v31
	v_fma_f32 v63, v63, v15, v31
	v_fma_f32 v48, v48, v16, v32
	v_fma_f32 v64, v64, v16, v32
	v_fma_f32 v49, v49, v17, v33
	v_fma_f32 v65, v65, v17, v33
	v_fma_f32 v50, v50, v18, v34
	v_fma_f32 v66, v66, v18, v34
	v_fma_f32 v51, v51, v19, v35
	v_fma_f32 v67, v67, v19, v35
	v_fma_f32 v52, v52, v20, v36
	v_fma_f32 v68, v68, v20, v36
	v_fma_f32 v53, v53, v21, v37
	v_fma_f32 v69, v69, v21, v37
	v_fma_f32 v54, v54, v22, v38
	v_fma_f32 v70, v70, v22, v38
	v_fma_f32 v55, v55, v23, v39
	v_fma_f32 v71, v71, v23, v39
	s_lshl_b32 s2, s11, 12
	s_add_u32 s16, s20, s2
	s_addc_u32 s17, s21, 0
	s_lshl_b32 s10, s15, 12
	s_add_u32 s18, s16, s10
	s_addc_u32 s19, s17, 0
	s_cmp_eq_u32 s14, 0
	s_cbranch_scc1 .Llna_nof32_p0
	global_store_dwordx4 v4, v[40:43], s[16:17]
	global_store_dwordx4 v4, v[44:47], s[16:17] offset:16
	global_store_dwordx4 v4, v[48:51], s[16:17] offset:2048
	global_store_dwordx4 v4, v[52:55], s[16:17] offset:2064
	global_store_dwordx4 v4, v[56:59], s[18:19]
	global_store_dwordx4 v4, v[60:63], s[18:19] offset:16
	global_store_dwordx4 v4, v[64:67], s[18:19] offset:2048
	global_store_dwordx4 v4, v[68:71], s[18:19] offset:2064
.Llna_nof32_p0:
	v_cvt_pk_bf16_f32 v112, v40, v41
	v_cvt_pk_bf16_f32 v113, v42, v43
	v_cvt_pk_bf16_f32 v114, v44, v45
	v_cvt_pk_bf16_f32 v115, v46, v47
	v_cvt_pk_bf16_f32 v116, v48, v49
	v_cvt_pk_bf16_f32 v117, v50, v51
	v_cvt_pk_bf16_f32 v118, v52, v53
	v_cvt_pk_bf16_f32 v119, v54, v55
	v_cvt_pk_bf16_f32 v120, v56, v57
	v_cvt_pk_bf16_f32 v121, v58, v59
	v_cvt_pk_bf16_f32 v122, v60, v61
	v_cvt_pk_bf16_f32 v123, v62, v63
	v_cvt_pk_bf16_f32 v124, v64, v65
	v_cvt_pk_bf16_f32 v125, v66, v67
	v_cvt_pk_bf16_f32 v126, v68, v69
	v_cvt_pk_bf16_f32 v127, v70, v71
	s_lshl_b32 s2, s11, 11
	s_add_u32 s16, s8, s2
	s_addc_u32 s17, s9, 0
	s_lshl_b32 s10, s15, 11
	s_add_u32 s18, s16, s10
	s_addc_u32 s19, s17, 0
	global_store_dwordx4 v5, v[112:115], s[16:17]
	global_store_dwordx4 v5, v[116:119], s[16:17] offset:1024
	global_store_dwordx4 v5, v[120:123], s[18:19]
	global_store_dwordx4 v5, v[124:127], s[18:19] offset:1024
	s_lshl_b32 s2, s11, 3
	s_add_u32 s16, s22, s2
	s_addc_u32 s17, s23, 0
	s_lshl_b32 s10, s15, 3
	s_add_u32 s18, s16, s10
	s_addc_u32 s19, s17, 0
	s_mov_b64 exec, 1
	global_store_dwordx2 v1, v[108:109], s[16:17]
	global_store_dwordx2 v1, v[110:111], s[18:19]
	s_mov_b64 exec, -1
; __device__ __forceinline__ void ln_phase(const PRef& P, const float* __restrict__ gw, const float* __restrict__ bw, bool write_f32) {
;   float* H = P.out(); bfr* hb = (bfr*)(P.ws() + WS_HB); float2* st = (float2*)(P.ws() + WS_MISC + MS_STATS);
;   const int lane = otid() & 63, wv = obid() * 8 + (otid() >> 6), nw = gridDim.x * 8;
;   for (int row = wv; row < TT; row += 2 * nw) {
;     float4* hp0 = (float4*)(H + (long)row * DM); float4* hp1 = (float4*)(H + (long)(row + nw) * DM); float4 v[2][4]; float s0 = 0.f, s1 = 0.f;
; #pragma unroll
;     for (int i = 0; i < 4; ++i) { v[0][i] = hp0[lane + 64 * i]; v[1][i] = hp1[lane + 64 * i]; }
; #pragma unroll
;     for (int i = 0; i < 4; ++i) { s0 += v[0][i].x + v[0][i].y + v[0][i].z + v[0][i].w; s1 += v[1][i].x + v[1][i].y + v[1][i].z + v[1][i].w; }
; #pragma unroll
;     for (int o = 32; o > 0; o >>= 1) { s0 += __shfl_xor(s0, o); s1 += __shfl_xor(s1, o); }
;     const float mu0 = s0 * (1.f / DM), mu1 = s1 * (1.f / DM); float q0 = 0.f, q1 = 0.f;
; #pragma unroll
;     for (int i = 0; i < 4; ++i) { float a = v[0][i].x - mu0, b = v[0][i].y - mu0, c = v[0][i].z - mu0, d = v[0][i].w - mu0; q0 += a * a + b * b + c * c + d * d;
;       float e = v[1][i].x - mu1, f = v[1][i].y - mu1, g = v[1][i].z - mu1, h = v[1][i].w - mu1; q1 += e * e + f * f + g * g + h * h; }
; #pragma unroll
;     for (int o = 32; o > 0; o >>= 1) { q0 += __shfl_xor(q0, o); q1 += __shfl_xor(q1, o); }
;     const float rs0 = rsqrtf(q0 * (1.f / DM) + 1e-5f), rs1 = rsqrtf(q1 * (1.f / DM) + 1e-5f);
;     if (lane == 0) { st[row] = make_float2(mu0, rs0); st[row + nw] = make_float2(mu1, rs1); }
; #pragma unroll
;     for (int i = 0; i < 4; ++i) { float4 g4 = ((const float4*)gw)[lane + 64 * i], b4 = ((const float4*)bw)[lane + 64 * i]; float4 o4, p4;
;       o4.x = (v[0][i].x - mu0) * rs0 * g4.x + b4.x; o4.y = (v[0][i].y - mu0) * rs0 * g4.y + b4.y; o4.z = (v[0][i].z - mu0) * rs0 * g4.z + b4.z; o4.w = (v[0][i].w - mu0) * rs0 * g4.w + b4.w;
;       p4.x = (v[1][i].x - mu1) * rs1 * g4.x + b4.x; p4.y = (v[1][i].y - mu1) * rs1 * g4.y + b4.y; p4.z = (v[1][i].z - mu1) * rs1 * g4.z + b4.z; p4.w = (v[1][i].w - mu1) * rs1 * g4.w + b4.w;
;       if (write_f32) { hp0[lane + 64 * i] = o4; hp1[lane + 64 * i] = p4; }
;       ((u32x2*)(hb + (long)row * DM))[lane + 64 * i] = u32x2{pk2(o4.x, o4.y), pk2(o4.z, o4.w)};
.Llna_loop:
	s_lshl_b32 s10, s15, 1
	s_add_u32 s11, s11, s10
	s_cmpk_ge_u32 s11, 0x8000
	s_cbranch_scc1 .Llna_done
	s_lshl_b32 s10, s15, 1
	s_add_u32 s10, s11, s10
	s_cmpk_lt_u32 s10, 0x8000
	s_cselect_b32 s10, s10, s11
	s_lshl_b32 s2, s10, 12
	s_add_u32 s16, s20, s2
	s_addc_u32 s17, s21, 0
	s_lshl_b32 s10, s15, 12
	s_add_u32 s18, s16, s10
	s_addc_u32 s19, s17, 0
	global_load_dwordx4 v[40:43], v4, s[16:17]
	global_load_dwordx4 v[44:47], v4, s[16:17] offset:16
	global_load_dwordx4 v[48:51], v4, s[16:17] offset:2048
	global_load_dwordx4 v[52:55], v4, s[16:17] offset:2064
	global_load_dwordx4 v[56:59], v4, s[18:19]
	global_load_dwordx4 v[60:63], v4, s[18:19] offset:16
	global_load_dwordx4 v[64:67], v4, s[18:19] offset:2048
	global_load_dwordx4 v[68:71], v4, s[18:19] offset:2064
	s_cmp_eq_u32 s14, 0
	s_cbranch_scc1 .Llna_w0
	s_waitcnt vmcnt(22)
	s_branch .Llna_x0
.Llna_w0:
	s_waitcnt vmcnt(14)
.Llna_x0:
	v_add_f32_e32 v104, v72, v73
	v_add_f32_e32 v105, v88, v89
	v_add_f32_e32 v104, v104, v74
	v_add_f32_e32 v105, v105, v90
	v_add_f32_e32 v104, v104, v75
	v_add_f32_e32 v105, v105, v91
	v_add_f32_e32 v104, v104, v76
	v_add_f32_e32 v105, v105, v92
	v_add_f32_e32 v104, v104, v77
	v_add_f32_e32 v105, v105, v93
	v_add_f32_e32 v104, v104, v78
	v_add_f32_e32 v105, v105, v94
	v_add_f32_e32 v104, v104, v79
	v_add_f32_e32 v105, v105, v95
	v_add_f32_e32 v104, v104, v80
	v_add_f32_e32 v105, v105, v96
	v_add_f32_e32 v104, v104, v81
	v_add_f32_e32 v105, v105, v97
	v_add_f32_e32 v104, v104, v82
	v_add_f32_e32 v105, v105, v98
	v_add_f32_e32 v104, v104, v83
	v_add_f32_e32 v105, v105, v99
	v_add_f32_e32 v104, v104, v84
	v_add_f32_e32 v105, v105, v100
	v_add_f32_e32 v104, v104, v85
	v_add_f32_e32 v105, v105, v101
	v_add_f32_e32 v104, v104, v86
	v_add_f32_e32 v105, v105, v102
	v_add_f32_e32 v104, v104, v87
	v_add_f32_e32 v105, v105, v103
	s_nop 1
	v_add_f32_dpp v104, v104, v104 quad_perm:[1,0,3,2] row_mask:0xf bank_mask:0xf
	v_add_f32_dpp v105, v105, v105 quad_perm:[1,0,3,2] row_mask:0xf bank_mask:0xf
	s_nop 1
	v_add_f32_dpp v104, v104, v104 quad_perm:[2,3,0,1] row_mask:0xf bank_mask:0xf
	v_add_f32_dpp v105, v105, v105 quad_perm:[2,3,0,1] row_mask:0xf bank_mask:0xf
	s_nop 1
	v_add_f32_dpp v104, v104, v104 row_half_mirror row_mask:0xf bank_mask:0xf
	v_add_f32_dpp v105, v105, v105 row_half_mirror row_mask:0xf bank_mask:0xf
	s_nop 1
	v_add_f32_dpp v104, v104, v104 row_mirror row_mask:0xf bank_mask:0xf
	v_add_f32_dpp v105, v105, v105 row_mirror row_mask:0xf bank_mask:0xf
	s_nop 1
	v_readlane_b32 s2, v104, 0
	v_readlane_b32 s10, v104, 16
	v_readlane_b32 s16, v104, 32
	v_readlane_b32 s17, v104, 48
	v_readlane_b32 s18, v105, 0
	v_readlane_b32 s19, v105, 16
	v_mov_b32_e32 v104, s2
	v_add_f32_e32 v104, s10, v104
	v_add_f32_e32 v104, s16, v104
	v_add_f32_e32 v104, s17, v104
	v_readlane_b32 s2, v105, 32
	v_readlane_b32 s10, v105, 48
	v_mov_b32_e32 v105, s18
	v_add_f32_e32 v105, s19, v105
	s_nop 0
	v_add_f32_e32 v105, s2, v105
	v_add_f32_e32 v105, s10, v105
	v_mul_f32_e32 v108, 0x3a800000, v104
	v_mul_f32_e32 v110, 0x3a800000, v105
	v_sub_f32_e32 v72, v72, v108
	v_sub_f32_e32 v88, v88, v110
	v_sub_f32_e32 v73, v73, v108
	v_sub_f32_e32 v89, v89, v110
	v_sub_f32_e32 v74, v74, v108
	v_sub_f32_e32 v90, v90, v110
	v_sub_f32_e32 v75, v75, v108
	v_sub_f32_e32 v91, v91, v110
	v_sub_f32_e32 v76, v76, v108
	v_sub_f32_e32 v92, v92, v110
	v_sub_f32_e32 v77, v77, v108
	v_sub_f32_e32 v93, v93, v110
	v_sub_f32_e32 v78, v78, v108
	v_sub_f32_e32 v94, v94, v110
	v_sub_f32_e32 v79, v79, v108
	v_sub_f32_e32 v95, v95, v110
	v_sub_f32_e32 v80, v80, v108
	v_sub_f32_e32 v96, v96, v110
	v_sub_f32_e32 v81, v81, v108
	v_sub_f32_e32 v97, v97, v110
	v_sub_f32_e32 v82, v82, v108
	v_sub_f32_e32 v98, v98, v110
	v_sub_f32_e32 v83, v83, v108
	v_sub_f32_e32 v99, v99, v110
	v_sub_f32_e32 v84, v84, v108
	v_sub_f32_e32 v100, v100, v110
	v_sub_f32_e32 v85, v85, v108
	v_sub_f32_e32 v101, v101, v110
	v_sub_f32_e32 v86, v86, v108
	v_sub_f32_e32 v102, v102, v110
	v_sub_f32_e32 v87, v87, v108
	v_sub_f32_e32 v103, v103, v110
	v_mul_f32_e32 v106, v72, v72
	v_mul_f32_e32 v107, v88, v88
	v_fmac_f32_e32 v106, v73, v73
	v_fmac_f32_e32 v107, v89, v89
	v_fmac_f32_e32 v106, v74, v74
	v_fmac_f32_e32 v107, v90, v90
	v_fmac_f32_e32 v106, v75, v75
	v_fmac_f32_e32 v107, v91, v91
	v_fmac_f32_e32 v106, v76, v76
	v_fmac_f32_e32 v107, v92, v92
	v_fmac_f32_e32 v106, v77, v77
	v_fmac_f32_e32 v107, v93, v93
	v_fmac_f32_e32 v106, v78, v78
	v_fmac_f32_e32 v107, v94, v94
	v_fmac_f32_e32 v106, v79, v79
	v_fmac_f32_e32 v107, v95, v95
	v_fmac_f32_e32 v106, v80, v80
	v_fmac_f32_e32 v107, v96, v96
	v_fmac_f32_e32 v106, v81, v81
	v_fmac_f32_e32 v107, v97, v97
	v_fmac_f32_e32 v106, v82, v82
	v_fmac_f32_e32 v107, v98, v98
	v_fmac_f32_e32 v106, v83, v83
	v_fmac_f32_e32 v107, v99, v99
	v_fmac_f32_e32 v106, v84, v84
	v_fmac_f32_e32 v107, v100, v100
	v_fmac_f32_e32 v106, v85, v85
	v_fmac_f32_e32 v107, v101, v101
	v_fmac_f32_e32 v106, v86, v86
	v_fmac_f32_e32 v107, v102, v102
	v_fmac_f32_e32 v106, v87, v87
	v_fmac_f32_e32 v107, v103, v103
	s_nop 1
	v_add_f32_dpp v106, v106, v106 quad_perm:[1,0,3,2] row_mask:0xf bank_mask:0xf
	v_add_f32_dpp v107, v107, v107 quad_perm:[1,0,3,2] row_mask:0xf bank_mask:0xf
	s_nop 1
	v_add_f32_dpp v106, v106, v106 quad_perm:[2,3,0,1] row_mask:0xf bank_mask:0xf
	v_add_f32_dpp v107, v107, v107 quad_perm:[2,3,0,1] row_mask:0xf bank_mask:0xf
	s_nop 1
	v_add_f32_dpp v106, v106, v106 row_half_mirror row_mask:0xf bank_mask:0xf
	v_add_f32_dpp v107, v107, v107 row_half_mirror row_mask:0xf bank_mask:0xf
; __device__ __forceinline__ void ln_phase(const PRef& P, const float* __restrict__ gw, const float* __restrict__ bw, bool write_f32) {
;   float* H = P.out(); bfr* hb = (bfr*)(P.ws() + WS_HB); float2* st = (float2*)(P.ws() + WS_MISC + MS_STATS);
;   const int lane = otid() & 63, wv = obid() * 8 + (otid() >> 6), nw = gridDim.x * 8;
;   for (int row = wv; row < TT; row += 2 * nw) {
;     float4* hp0 = (float4*)(H + (long)row * DM); float4* hp1 = (float4*)(H + (long)(row + nw) * DM); float4 v[2][4]; float s0 = 0.f, s1 = 0.f;
; #pragma unroll
;     for (int i = 0; i < 4; ++i) { v[0][i] = hp0[lane + 64 * i]; v[1][i] = hp1[lane + 64 * i]; }
; #pragma unroll
;     for (int i = 0; i < 4; ++i) { s0 += v[0][i].x + v[0][i].y + v[0][i].z + v[0][i].w; s1 += v[1][i].x + v[1][i].y + v[1][i].z + v[1][i].w; }
; #pragma unroll
;     for (int o = 32; o > 0; o >>= 1) { s0 += __shfl_xor(s0, o); s1 += __shfl_xor(s1, o); }
;     const float mu0 = s0 * (1.f / DM), mu1 = s1 * (1.f / DM); float q0 = 0.f, q1 = 0.f;
; #pragma unroll
;     for (int i = 0; i < 4; ++i) { float a = v[0][i].x - mu0, b = v[0][i].y - mu0, c = v[0][i].z - mu0, d = v[0][i].w - mu0; q0 += a * a + b * b + c * c + d * d;
;       float e = v[1][i].x - mu1, f = v[1][i].y - mu1, g = v[1][i].z - mu1, h = v[1][i].w - mu1; q1 += e * e + f * f + g * g + h * h; }
; #pragma unroll
;     for (int o = 32; o > 0; o >>= 1) { q0 += __shfl_xor(q0, o); q1 += __shfl_xor(q1, o); }
;     const float rs0 = rsqrtf(q0 * (1.f / DM) + 1e-5f), rs1 = rsqrtf(q1 * (1.f / DM) + 1e-5f);
;     if (lane == 0) { st[row] = make_float2(mu0, rs0); st[row + nw] = make_float2(mu1, rs1); }
; #pragma unroll
;     for (int i = 0; i < 4; ++i) { float4 g4 = ((const float4*)gw)[lane + 64 * i], b4 = ((const float4*)bw)[lane + 64 * i]; float4 o4, p4;
;       o4.x = (v[0][i].x - mu0) * rs0 * g4.x + b4.x; o4.y = (v[0][i].y - mu0) * rs0 * g4.y + b4.y; o4.z = (v[0][i].z - mu0) * rs0 * g4.z + b4.z; o4.w = (v[0][i].w - mu0) * rs0 * g4.w + b4.w;
;       p4.x = (v[1][i].x - mu1) * rs1 * g4.x + b4.x; p4.y = (v[1][i].y - mu1) * rs1 * g4.y + b4.y; p4.z = (v[1][i].z - mu1) * rs1 * g4.z + b4.z; p4.w = (v[1][i].w - mu1) * rs1 * g4.w + b4.w;
;       if (write_f32) { hp0[lane + 64 * i] = o4; hp1[lane + 64 * i] = p4; }
;       ((u32x2*)(hb + (long)row * DM))[lane + 64 * i] = u32x2{pk2(o4.x, o4.y), pk2(o4.z, o4.w)};
	s_nop 1
	v_add_f32_dpp v106, v106, v106 row_mirror row_mask:0xf bank_mask:0xf
	v_add_f32_dpp v107, v107, v107 row_mirror row_mask:0xf bank_mask:0xf
	s_nop 1
	v_readlane_b32 s2, v106, 0
	v_readlane_b32 s10, v106, 16
	v_readlane_b32 s16, v106, 32
	v_readlane_b32 s17, v106, 48
	v_readlane_b32 s18, v107, 0
	v_readlane_b32 s19, v107, 16
	v_mov_b32_e32 v106, s2
	v_add_f32_e32 v106, s10, v106
	v_add_f32_e32 v106, s16, v106
	v_add_f32_e32 v106, s17, v106
	v_readlane_b32 s2, v107, 32
	v_readlane_b32 s10, v107, 48
	v_mov_b32_e32 v107, s18
	v_add_f32_e32 v107, s19, v107
	s_nop 0
	v_add_f32_e32 v107, s2, v107
	v_add_f32_e32 v107, s10, v107
	v_mul_f32_e32 v106, 0x3a800000, v106
	v_mul_f32_e32 v107, 0x3a800000, v107
	v_add_f32_e32 v106, 0x3727c5ac, v106
	v_add_f32_e32 v107, 0x3727c5ac, v107
	v_rsq_f32_e32 v109, v106
	v_rsq_f32_e32 v111, v107
	s_nop 0
	v_mul_f32_e32 v72, v72, v109
	v_mul_f32_e32 v88, v88, v111
	v_mul_f32_e32 v73, v73, v109
	v_mul_f32_e32 v89, v89, v111
	v_mul_f32_e32 v74, v74, v109
	v_mul_f32_e32 v90, v90, v111
	v_mul_f32_e32 v75, v75, v109
	v_mul_f32_e32 v91, v91, v111
	v_mul_f32_e32 v76, v76, v109
	v_mul_f32_e32 v92, v92, v111
	v_mul_f32_e32 v77, v77, v109
	v_mul_f32_e32 v93, v93, v111
	v_mul_f32_e32 v78, v78, v109
	v_mul_f32_e32 v94, v94, v111
	v_mul_f32_e32 v79, v79, v109
	v_mul_f32_e32 v95, v95, v111
	v_mul_f32_e32 v80, v80, v109
	v_mul_f32_e32 v96, v96, v111
	v_mul_f32_e32 v81, v81, v109
	v_mul_f32_e32 v97, v97, v111
	v_mul_f32_e32 v82, v82, v109
	v_mul_f32_e32 v98, v98, v111
	v_mul_f32_e32 v83, v83, v109
	v_mul_f32_e32 v99, v99, v111
	v_mul_f32_e32 v84, v84, v109
	v_mul_f32_e32 v100, v100, v111
	v_mul_f32_e32 v85, v85, v109
	v_mul_f32_e32 v101, v101, v111
	v_mul_f32_e32 v86, v86, v109
	v_mul_f32_e32 v102, v102, v111
	v_mul_f32_e32 v87, v87, v109
	v_mul_f32_e32 v103, v103, v111
	v_fma_f32 v72, v72, v8, v24
	v_fma_f32 v88, v88, v8, v24
	v_fma_f32 v73, v73, v9, v25
	v_fma_f32 v89, v89, v9, v25
	v_fma_f32 v74, v74, v10, v26
	v_fma_f32 v90, v90, v10, v26
	v_fma_f32 v75, v75, v11, v27
	v_fma_f32 v91, v91, v11, v27
	v_fma_f32 v76, v76, v12, v28
	v_fma_f32 v92, v92, v12, v28
	v_fma_f32 v77, v77, v13, v29
	v_fma_f32 v93, v93, v13, v29
	v_fma_f32 v78, v78, v14, v30
	v_fma_f32 v94, v94, v14, v30
	v_fma_f32 v79, v79, v15, v31
	v_fma_f32 v95, v95, v15, v31
	v_fma_f32 v80, v80, v16, v32
	v_fma_f32 v96, v96, v16, v32
	v_fma_f32 v81, v81, v17, v33
	v_fma_f32 v97, v97, v17, v33
	v_fma_f32 v82, v82, v18, v34
	v_fma_f32 v98, v98, v18, v34
	v_fma_f32 v83, v83, v19, v35
	v_fma_f32 v99, v99, v19, v35
	v_fma_f32 v84, v84, v20, v36
	v_fma_f32 v100, v100, v20, v36
	v_fma_f32 v85, v85, v21, v37
	v_fma_f32 v101, v101, v21, v37
	v_fma_f32 v86, v86, v22, v38
	v_fma_f32 v102, v102, v22, v38
	v_fma_f32 v87, v87, v23, v39
	v_fma_f32 v103, v103, v23, v39
	s_lshl_b32 s2, s11, 12
	s_add_u32 s16, s20, s2
	s_addc_u32 s17, s21, 0
	s_lshl_b32 s10, s15, 12
	s_add_u32 s18, s16, s10
	s_addc_u32 s19, s17, 0
	s_cmp_eq_u32 s14, 0
	s_cbranch_scc1 .Llna_nof32_p1
	global_store_dwordx4 v4, v[72:75], s[16:17]
	global_store_dwordx4 v4, v[76:79], s[16:17] offset:16
	global_store_dwordx4 v4, v[80:83], s[16:17] offset:2048
	global_store_dwordx4 v4, v[84:87], s[16:17] offset:2064
	global_store_dwordx4 v4, v[88:91], s[18:19]
	global_store_dwordx4 v4, v[92:95], s[18:19] offset:16
	global_store_dwordx4 v4, v[96:99], s[18:19] offset:2048
	global_store_dwordx4 v4, v[100:103], s[18:19] offset:2064
.Llna_nof32_p1:
	v_cvt_pk_bf16_f32 v112, v72, v73
	v_cvt_pk_bf16_f32 v113, v74, v75
	v_cvt_pk_bf16_f32 v114, v76, v77
	v_cvt_pk_bf16_f32 v115, v78, v79
	v_cvt_pk_bf16_f32 v116, v80, v81
	v_cvt_pk_bf16_f32 v117, v82, v83
	v_cvt_pk_bf16_f32 v118, v84, v85
	v_cvt_pk_bf16_f32 v119, v86, v87
	v_cvt_pk_bf16_f32 v120, v88, v89
	v_cvt_pk_bf16_f32 v121, v90, v91
	v_cvt_pk_bf16_f32 v122, v92, v93
	v_cvt_pk_bf16_f32 v123, v94, v95
	v_cvt_pk_bf16_f32 v124, v96, v97
	v_cvt_pk_bf16_f32 v125, v98, v99
	v_cvt_pk_bf16_f32 v126, v100, v101
	v_cvt_pk_bf16_f32 v127, v102, v103
	s_lshl_b32 s2, s11, 11
	s_add_u32 s16, s8, s2
	s_addc_u32 s17, s9, 0
	s_lshl_b32 s10, s15, 11
	s_add_u32 s18, s16, s10
	s_addc_u32 s19, s17, 0
	global_store_dwordx4 v5, v[112:115], s[16:17]
	global_store_dwordx4 v5, v[116:119], s[16:17] offset:1024
	global_store_dwordx4 v5, v[120:123], s[18:19]
	global_store_dwordx4 v5, v[124:127], s[18:19] offset:1024
	s_lshl_b32 s2, s11, 3
	s_add_u32 s16, s22, s2
	s_addc_u32 s17, s23, 0
	s_lshl_b32 s10, s15, 3
	s_add_u32 s18, s16, s10
	s_addc_u32 s19, s17, 0
	s_mov_b64 exec, 1
	global_store_dwordx2 v1, v[108:109], s[16:17]
	global_store_dwordx2 v1, v[110:111], s[18:19]
	s_mov_b64 exec, -1
	s_lshl_b32 s10, s15, 1
	s_add_u32 s11, s11, s10
	s_cmpk_ge_u32 s11, 0x8000
	s_cbranch_scc1 .Llna_done
	s_lshl_b32 s10, s15, 1
	s_add_u32 s10, s11, s10
	s_cmpk_lt_u32 s10, 0x8000
	s_cselect_b32 s10, s10, s11
	s_lshl_b32 s2, s10, 12
	s_add_u32 s16, s20, s2
	s_addc_u32 s17, s21, 0
	s_lshl_b32 s10, s15, 12
	s_add_u32 s18, s16, s10
	s_addc_u32 s19, s17, 0
	global_load_dwordx4 v[72:75], v4, s[16:17]
	global_load_dwordx4 v[76:79], v4, s[16:17] offset:16
	global_load_dwordx4 v[80:83], v4, s[16:17] offset:2048
	global_load_dwordx4 v[84:87], v4, s[16:17] offset:2064
	global_load_dwordx4 v[88:91], v4, s[18:19]
	global_load_dwordx4 v[92:95], v4, s[18:19] offset:16
	global_load_dwordx4 v[96:99], v4, s[18:19] offset:2048
	global_load_dwordx4 v[100:103], v4, s[18:19] offset:2064
	s_cmp_eq_u32 s14, 0
	s_cbranch_scc1 .Llna_w1
	s_waitcnt vmcnt(22)
	s_branch .Llna_x1

; __device__ __forceinline__ void ln_phase(const PRef& P, const float* __restrict__ gw, const float* __restrict__ bw, bool write_f32) {
;     ...
;     for (int i = 0; i < 4; ++i) { s0 += v[0][i].x + v[0][i].y + v[0][i].z + v[0][i].w; s1 += v[1][i].x + v[1][i].y + v[1][i].z + v[1][i].w; }
; #pragma unroll
;     for (int o = 32; o > 0; o >>= 1) { s0 += __shfl_xor(s0, o); s1 += __shfl_xor(s1, o); }
;     const float mu0 = s0 * (1.f / DM), mu1 = s1 * (1.f / DM); float q0 = 0.f, q1 = 0.f;
; #pragma unroll
;     for (int i = 0; i < 4; ++i) { float a = v[0][i].x - mu0, b = v[0][i].y - mu0, c = v[0][i].z - mu0, d = v[0][i].w - mu0; q0 += a * a + b * b + c * c + d * d;
;       float e = v[1][i].x - mu1, f = v[1][i].y - mu1, g = v[1][i].z - mu1, h = v[1][i].w - mu1; q1 += e * e + f * f + g * g + h * h; }
; #pragma unroll
;     for (int o = 32; o > 0; o >>= 1) { q0 += __shfl_xor(q0, o); q1 += __shfl_xor(q1, o); }
.Llna_x1:
	v_add_f32_e32 v104, v40, v41
	v_add_f32_e32 v105, v56, v57
	v_add_f32_e32 v104, v104, v42
	v_add_f32_e32 v105, v105, v58
	v_add_f32_e32 v104, v104, v43
	v_add_f32_e32 v105, v105, v59
	v_add_f32_e32 v104, v104, v44
	v_add_f32_e32 v105, v105, v60
	v_add_f32_e32 v104, v104, v45
	v_add_f32_e32 v105, v105, v61
	v_add_f32_e32 v104, v104, v46
	v_add_f32_e32 v105, v105, v62
	v_add_f32_e32 v104, v104, v47
	v_add_f32_e32 v105, v105, v63
	v_add_f32_e32 v104, v104, v48
	v_add_f32_e32 v105, v105, v64
	v_add_f32_e32 v104, v104, v49
	v_add_f32_e32 v105, v105, v65
	v_add_f32_e32 v104, v104, v50
	v_add_f32_e32 v105, v105, v66
	v_add_f32_e32 v104, v104, v51
	v_add_f32_e32 v105, v105, v67
	v_add_f32_e32 v104, v104, v52
	v_add_f32_e32 v105, v105, v68
	v_add_f32_e32 v104, v104, v53
	v_add_f32_e32 v105, v105, v69
	v_add_f32_e32 v104, v104, v54
	v_add_f32_e32 v105, v105, v70
	v_add_f32_e32 v104, v104, v55
	v_add_f32_e32 v105, v105, v71
	s_nop 1
	v_add_f32_dpp v104, v104, v104 quad_perm:[1,0,3,2] row_mask:0xf bank_mask:0xf
	v_add_f32_dpp v105, v105, v105 quad_perm:[1,0,3,2] row_mask:0xf bank_mask:0xf
	s_nop 1
	v_add_f32_dpp v104, v104, v104 quad_perm:[2,3,0,1] row_mask:0xf bank_mask:0xf
	v_add_f32_dpp v105, v105, v105 quad_perm:[2,3,0,1] row_mask:0xf bank_mask:0xf
	s_nop 1
	v_add_f32_dpp v104, v104, v104 row_half_mirror row_mask:0xf bank_mask:0xf
	v_add_f32_dpp v105, v105, v105 row_half_mirror row_mask:0xf bank_mask:0xf
	s_nop 1
	v_add_f32_dpp v104, v104, v104 row_mirror row_mask:0xf bank_mask:0xf
	v_add_f32_dpp v105, v105, v105 row_mirror row_mask:0xf bank_mask:0xf
	s_nop 1
	v_readlane_b32 s2, v104, 0
	v_readlane_b32 s10, v104, 16
	v_readlane_b32 s16, v104, 32
	v_readlane_b32 s17, v104, 48
	v_readlane_b32 s18, v105, 0
	v_readlane_b32 s19, v105, 16
	v_mov_b32_e32 v104, s2
	v_add_f32_e32 v104, s10, v104
	v_add_f32_e32 v104, s16, v104
	v_add_f32_e32 v104, s17, v104
	v_readlane_b32 s2, v105, 32
	v_readlane_b32 s10, v105, 48
	v_mov_b32_e32 v105, s18
	v_add_f32_e32 v105, s19, v105
	s_nop 0
	v_add_f32_e32 v105, s2, v105
	v_add_f32_e32 v105, s10, v105
	v_mul_f32_e32 v108, 0x3a800000, v104
	v_mul_f32_e32 v110, 0x3a800000, v105
	v_sub_f32_e32 v40, v40, v108
	v_sub_f32_e32 v56, v56, v110
	v_sub_f32_e32 v41, v41, v108
	v_sub_f32_e32 v57, v57, v110
	v_sub_f32_e32 v42, v42, v108
	v_sub_f32_e32 v58, v58, v110
	v_sub_f32_e32 v43, v43, v108
	v_sub_f32_e32 v59, v59, v110
	v_sub_f32_e32 v44, v44, v108
	v_sub_f32_e32 v60, v60, v110
	v_sub_f32_e32 v45, v45, v108
	v_sub_f32_e32 v61, v61, v110
	v_sub_f32_e32 v46, v46, v108
	v_sub_f32_e32 v62, v62, v110
	v_sub_f32_e32 v47, v47, v108
	v_sub_f32_e32 v63, v63, v110
	v_sub_f32_e32 v48, v48, v108
	v_sub_f32_e32 v64, v64, v110
	v_sub_f32_e32 v49, v49, v108
	v_sub_f32_e32 v65, v65, v110
	v_sub_f32_e32 v50, v50, v108
	v_sub_f32_e32 v66, v66, v110
	v_sub_f32_e32 v51, v51, v108
	v_sub_f32_e32 v67, v67, v110
	v_sub_f32_e32 v52, v52, v108
	v_sub_f32_e32 v68, v68, v110
	v_sub_f32_e32 v53, v53, v108
	v_sub_f32_e32 v69, v69, v110
	v_sub_f32_e32 v54, v54, v108
	v_sub_f32_e32 v70, v70, v110
	v_sub_f32_e32 v55, v55, v108
	v_sub_f32_e32 v71, v71, v110
	v_mul_f32_e32 v106, v40, v40
	v_mul_f32_e32 v107, v56, v56
	v_fmac_f32_e32 v106, v41, v41
	v_fmac_f32_e32 v107, v57, v57
	v_fmac_f32_e32 v106, v42, v42
	v_fmac_f32_e32 v107, v58, v58
	v_fmac_f32_e32 v106, v43, v43
	v_fmac_f32_e32 v107, v59, v59
	v_fmac_f32_e32 v106, v44, v44
	v_fmac_f32_e32 v107, v60, v60
	v_fmac_f32_e32 v106, v45, v45
	v_fmac_f32_e32 v107, v61, v61
	v_fmac_f32_e32 v106, v46, v46
	v_fmac_f32_e32 v107, v62, v62
	v_fmac_f32_e32 v106, v47, v47
	v_fmac_f32_e32 v107, v63, v63
	v_fmac_f32_e32 v106, v48, v48
	v_fmac_f32_e32 v107, v64, v64
	v_fmac_f32_e32 v106, v49, v49
	v_fmac_f32_e32 v107, v65, v65
	v_fmac_f32_e32 v106, v50, v50
	v_fmac_f32_e32 v107, v66, v66
	v_fmac_f32_e32 v106, v51, v51
	v_fmac_f32_e32 v107, v67, v67
	v_fmac_f32_e32 v106, v52, v52
	v_fmac_f32_e32 v107, v68, v68
	v_fmac_f32_e32 v106, v53, v53
	v_fmac_f32_e32 v107, v69, v69
	v_fmac_f32_e32 v106, v54, v54
	v_fmac_f32_e32 v107, v70, v70
	v_fmac_f32_e32 v106, v55, v55
	v_fmac_f32_e32 v107, v71, v71
	s_nop 1
	v_add_f32_dpp v106, v106, v106 quad_perm:[1,0,3,2] row_mask:0xf bank_mask:0xf
	v_add_f32_dpp v107, v107, v107 quad_perm:[1,0,3,2] row_mask:0xf bank_mask:0xf
	s_nop 1
	v_add_f32_dpp v106, v106, v106 quad_perm:[2,3,0,1] row_mask:0xf bank_mask:0xf
	v_add_f32_dpp v107, v107, v107 quad_perm:[2,3,0,1] row_mask:0xf bank_mask:0xf
	s_nop 1
	v_add_f32_dpp v106, v106, v106 row_half_mirror row_mask:0xf bank_mask:0xf
	v_add_f32_dpp v107, v107, v107 row_half_mirror row_mask:0xf bank_mask:0xf
	s_nop 1
; __device__ __forceinline__ void ln_phase(const PRef& P, const float* __restrict__ gw, const float* __restrict__ bw, bool write_f32) {
;   float* H = P.out(); bfr* hb = (bfr*)(P.ws() + WS_HB); float2* st = (float2*)(P.ws() + WS_MISC + MS_STATS);
;   const int lane = otid() & 63, wv = obid() * 8 + (otid() >> 6), nw = gridDim.x * 8;
;   for (int row = wv; row < TT; row += 2 * nw) {
;     float4* hp0 = (float4*)(H + (long)row * DM); float4* hp1 = (float4*)(H + (long)(row + nw) * DM); float4 v[2][4]; float s0 = 0.f, s1 = 0.f;
; #pragma unroll
;     for (int i = 0; i < 4; ++i) { v[0][i] = hp0[lane + 64 * i]; v[1][i] = hp1[lane + 64 * i]; }
; #pragma unroll
;     for (int i = 0; i < 4; ++i) { s0 += v[0][i].x + v[0][i].y + v[0][i].z + v[0][i].w; s1 += v[1][i].x + v[1][i].y + v[1][i].z + v[1][i].w; }
; #pragma unroll
;     for (int o = 32; o > 0; o >>= 1) { s0 += __shfl_xor(s0, o); s1 += __shfl_xor(s1, o); }
;     const float mu0 = s0 * (1.f / DM), mu1 = s1 * (1.f / DM); float q0 = 0.f, q1 = 0.f;
; #pragma unroll
;     for (int i = 0; i < 4; ++i) { float a = v[0][i].x - mu0, b = v[0][i].y - mu0, c = v[0][i].z - mu0, d = v[0][i].w - mu0; q0 += a * a + b * b + c * c + d * d;
;       float e = v[1][i].x - mu1, f = v[1][i].y - mu1, g = v[1][i].z - mu1, h = v[1][i].w - mu1; q1 += e * e + f * f + g * g + h * h; }
; #pragma unroll
;     for (int o = 32; o > 0; o >>= 1) { q0 += __shfl_xor(q0, o); q1 += __shfl_xor(q1, o); }
;     const float rs0 = rsqrtf(q0 * (1.f / DM) + 1e-5f), rs1 = rsqrtf(q1 * (1.f / DM) + 1e-5f);
;     if (lane == 0) { st[row] = make_float2(mu0, rs0); st[row + nw] = make_float2(mu1, rs1); }
; #pragma unroll
;     for (int i = 0; i < 4; ++i) { float4 g4 = ((const float4*)gw)[lane + 64 * i], b4 = ((const float4*)bw)[lane + 64 * i]; float4 o4, p4;
;       o4.x = (v[0][i].x - mu0) * rs0 * g4.x + b4.x; o4.y = (v[0][i].y - mu0) * rs0 * g4.y + b4.y; o4.z = (v[0][i].z - mu0) * rs0 * g4.z + b4.z; o4.w = (v[0][i].w - mu0) * rs0 * g4.w + b4.w;
;       p4.x = (v[1][i].x - mu1) * rs1 * g4.x + b4.x; p4.y = (v[1][i].y - mu1) * rs1 * g4.y + b4.y; p4.z = (v[1][i].z - mu1) * rs1 * g4.z + b4.z; p4.w = (v[1][i].w - mu1) * rs1 * g4.w + b4.w;
;       if (write_f32) { hp0[lane + 64 * i] = o4; hp1[lane + 64 * i] = p4; }
;       ((u32x2*)(hb + (long)row * DM))[lane + 64 * i] = u32x2{pk2(o4.x, o4.y), pk2(o4.z, o4.w)};
	v_add_f32_dpp v106, v106, v106 row_mirror row_mask:0xf bank_mask:0xf
	v_add_f32_dpp v107, v107, v107 row_mirror row_mask:0xf bank_mask:0xf
	s_nop 1
	v_readlane_b32 s2, v106, 0
	v_readlane_b32 s10, v106, 16
	v_readlane_b32 s16, v106, 32
	v_readlane_b32 s17, v106, 48
	v_readlane_b32 s18, v107, 0
	v_readlane_b32 s19, v107, 16
	v_mov_b32_e32 v106, s2
	v_add_f32_e32 v106, s10, v106
	v_add_f32_e32 v106, s16, v106
	v_add_f32_e32 v106, s17, v106
	v_readlane_b32 s2, v107, 32
	v_readlane_b32 s10, v107, 48
	v_mov_b32_e32 v107, s18
	v_add_f32_e32 v107, s19, v107
	s_nop 0
	v_add_f32_e32 v107, s2, v107
	v_add_f32_e32 v107, s10, v107
	v_mul_f32_e32 v106, 0x3a800000, v106
	v_mul_f32_e32 v107, 0x3a800000, v107
	v_add_f32_e32 v106, 0x3727c5ac, v106
	v_add_f32_e32 v107, 0x3727c5ac, v107
	v_rsq_f32_e32 v109, v106
	v_rsq_f32_e32 v111, v107
	s_nop 0
	v_mul_f32_e32 v40, v40, v109
	v_mul_f32_e32 v56, v56, v111
	v_mul_f32_e32 v41, v41, v109
	v_mul_f32_e32 v57, v57, v111
	v_mul_f32_e32 v42, v42, v109
	v_mul_f32_e32 v58, v58, v111
	v_mul_f32_e32 v43, v43, v109
	v_mul_f32_e32 v59, v59, v111
	v_mul_f32_e32 v44, v44, v109
	v_mul_f32_e32 v60, v60, v111
	v_mul_f32_e32 v45, v45, v109
	v_mul_f32_e32 v61, v61, v111
	v_mul_f32_e32 v46, v46, v109
	v_mul_f32_e32 v62, v62, v111
	v_mul_f32_e32 v47, v47, v109
	v_mul_f32_e32 v63, v63, v111
	v_mul_f32_e32 v48, v48, v109
	v_mul_f32_e32 v64, v64, v111
	v_mul_f32_e32 v49, v49, v109
	v_mul_f32_e32 v65, v65, v111
	v_mul_f32_e32 v50, v50, v109
	v_mul_f32_e32 v66, v66, v111
	v_mul_f32_e32 v51, v51, v109
	v_mul_f32_e32 v67, v67, v111
	v_mul_f32_e32 v52, v52, v109
	v_mul_f32_e32 v68, v68, v111
	v_mul_f32_e32 v53, v53, v109
	v_mul_f32_e32 v69, v69, v111
	v_mul_f32_e32 v54, v54, v109
	v_mul_f32_e32 v70, v70, v111
	v_mul_f32_e32 v55, v55, v109
	v_mul_f32_e32 v71, v71, v111
	v_fma_f32 v40, v40, v8, v24
	v_fma_f32 v56, v56, v8, v24
	v_fma_f32 v41, v41, v9, v25
	v_fma_f32 v57, v57, v9, v25
	v_fma_f32 v42, v42, v10, v26
	v_fma_f32 v58, v58, v10, v26
	v_fma_f32 v43, v43, v11, v27
	v_fma_f32 v59, v59, v11, v27
	v_fma_f32 v44, v44, v12, v28
	v_fma_f32 v60, v60, v12, v28
	v_fma_f32 v45, v45, v13, v29
	v_fma_f32 v61, v61, v13, v29
	v_fma_f32 v46, v46, v14, v30
	v_fma_f32 v62, v62, v14, v30
	v_fma_f32 v47, v47, v15, v31
	v_fma_f32 v63, v63, v15, v31
	v_fma_f32 v48, v48, v16, v32
	v_fma_f32 v64, v64, v16, v32
	v_fma_f32 v49, v49, v17, v33
	v_fma_f32 v65, v65, v17, v33
	v_fma_f32 v50, v50, v18, v34
	v_fma_f32 v66, v66, v18, v34
	v_fma_f32 v51, v51, v19, v35
	v_fma_f32 v67, v67, v19, v35
	v_fma_f32 v52, v52, v20, v36
	v_fma_f32 v68, v68, v20, v36
	v_fma_f32 v53, v53, v21, v37
	v_fma_f32 v69, v69, v21, v37
	v_fma_f32 v54, v54, v22, v38
	v_fma_f32 v70, v70, v22, v38
	v_fma_f32 v55, v55, v23, v39
	v_fma_f32 v71, v71, v23, v39
	s_lshl_b32 s2, s11, 12
	s_add_u32 s16, s20, s2
	s_addc_u32 s17, s21, 0
	s_lshl_b32 s10, s15, 12
	s_add_u32 s18, s16, s10
	s_addc_u32 s19, s17, 0
	s_cmp_eq_u32 s14, 0
	s_cbranch_scc1 .Llna_nof32_p2
	global_store_dwordx4 v4, v[40:43], s[16:17]
	global_store_dwordx4 v4, v[44:47], s[16:17] offset:16
	global_store_dwordx4 v4, v[48:51], s[16:17] offset:2048
	global_store_dwordx4 v4, v[52:55], s[16:17] offset:2064
	global_store_dwordx4 v4, v[56:59], s[18:19]
	global_store_dwordx4 v4, v[60:63], s[18:19] offset:16
	global_store_dwordx4 v4, v[64:67], s[18:19] offset:2048
	global_store_dwordx4 v4, v[68:71], s[18:19] offset:2064
.Llna_nof32_p2:
	v_cvt_pk_bf16_f32 v112, v40, v41
	v_cvt_pk_bf16_f32 v113, v42, v43
	v_cvt_pk_bf16_f32 v114, v44, v45
	v_cvt_pk_bf16_f32 v115, v46, v47
	v_cvt_pk_bf16_f32 v116, v48, v49
	v_cvt_pk_bf16_f32 v117, v50, v51
	v_cvt_pk_bf16_f32 v118, v52, v53
	v_cvt_pk_bf16_f32 v119, v54, v55
	v_cvt_pk_bf16_f32 v120, v56, v57
	v_cvt_pk_bf16_f32 v121, v58, v59
	v_cvt_pk_bf16_f32 v122, v60, v61
	v_cvt_pk_bf16_f32 v123, v62, v63
	v_cvt_pk_bf16_f32 v124, v64, v65
	v_cvt_pk_bf16_f32 v125, v66, v67
	v_cvt_pk_bf16_f32 v126, v68, v69
	v_cvt_pk_bf16_f32 v127, v70, v71
	s_lshl_b32 s2, s11, 11
	s_add_u32 s16, s8, s2
	s_addc_u32 s17, s9, 0
	s_lshl_b32 s10, s15, 11
	s_add_u32 s18, s16, s10
	s_addc_u32 s19, s17, 0
	global_store_dwordx4 v5, v[112:115], s[16:17]
	global_store_dwordx4 v5, v[116:119], s[16:17] offset:1024
	global_store_dwordx4 v5, v[120:123], s[18:19]
	global_store_dwordx4 v5, v[124:127], s[18:19] offset:1024
	s_lshl_b32 s2, s11, 3
	s_add_u32 s16, s22, s2
	s_addc_u32 s17, s23, 0
	s_lshl_b32 s10, s15, 3
	s_add_u32 s18, s16, s10
	s_addc_u32 s19, s17, 0
	s_mov_b64 exec, 1
	global_store_dwordx2 v1, v[108:109], s[16:17]
	global_store_dwordx2 v1, v[110:111], s[18:19]
	s_mov_b64 exec, -1
	s_branch .Llna_loop

; __device__ __forceinline__ void ln_phase(const PRef& P, const float* __restrict__ gw, const float* __restrict__ bw, bool write_f32) {
;   float* H = P.out(); bfr* hb = (bfr*)(P.ws() + WS_HB); float2* st = (float2*)(P.ws() + WS_MISC + MS_STATS);
;   const int lane = otid() & 63, wv = obid() * 8 + (otid() >> 6), nw = gridDim.x * 8;
;   for (int row = wv; row < TT; row += 2 * nw) {
;     float4* hp0 = (float4*)(H + (long)row * DM); float4* hp1 = (float4*)(H + (long)(row + nw) * DM); float4 v[2][4]; float s0 = 0.f, s1 = 0.f;
; #pragma unroll
;     for (int i = 0; i < 4; ++i) { v[0][i] = hp0[lane + 64 * i]; v[1][i] = hp1[lane + 64 * i]; }
; #pragma unroll
;     for (int i = 0; i < 4; ++i) { s0 += v[0][i].x + v[0][i].y + v[0][i].z + v[0][i].w; s1 += v[1][i].x + v[1][i].y + v[1][i].z + v[1][i].w; }
; #pragma unroll
;     for (int o = 32; o > 0; o >>= 1) { s0 += __shfl_xor(s0, o); s1 += __shfl_xor(s1, o); }
;     const float mu0 = s0 * (1.f / DM), mu1 = s1 * (1.f / DM); float q0 = 0.f, q1 = 0.f;
; #pragma unroll
;     for (int i = 0; i < 4; ++i) { float a = v[0][i].x - mu0, b = v[0][i].y - mu0, c = v[0][i].z - mu0, d = v[0][i].w - mu0; q0 += a * a + b * b + c * c + d * d;
;       float e = v[1][i].x - mu1, f = v[1][i].y - mu1, g = v[1][i].z - mu1, h = v[1][i].w - mu1; q1 += e * e + f * f + g * g + h * h; }
; #pragma unroll
;     for (int o = 32; o > 0; o >>= 1) { q0 += __shfl_xor(q0, o); q1 += __shfl_xor(q1, o); }
;     const float rs0 = rsqrtf(q0 * (1.f / DM) + 1e-5f), rs1 = rsqrtf(q1 * (1.f / DM) + 1e-5f);
;     if (lane == 0) { st[row] = make_float2(mu0, rs0); st[row + nw] = make_float2(mu1, rs1); }
; #pragma unroll
;     for (int i = 0; i < 4; ++i) { float4 g4 = ((const float4*)gw)[lane + 64 * i], b4 = ((const float4*)bw)[lane + 64 * i]; float4 o4, p4;
;       o4.x = (v[0][i].x - mu0) * rs0 * g4.x + b4.x; o4.y = (v[0][i].y - mu0) * rs0 * g4.y + b4.y; o4.z = (v[0][i].z - mu0) * rs0 * g4.z + b4.z; o4.w = (v[0][i].w - mu0) * rs0 * g4.w + b4.w;
;       p4.x = (v[1][i].x - mu1) * rs1 * g4.x + b4.x; p4.y = (v[1][i].y - mu1) * rs1 * g4.y + b4.y; p4.z = (v[1][i].z - mu1) * rs1 * g4.z + b4.z; p4.w = (v[1][i].w - mu1) * rs1 * g4.w + b4.w;
;       if (write_f32) { hp0[lane + 64 * i] = o4; hp1[lane + 64 * i] = p4; }
;       ((u32x2*)(hb + (long)row * DM))[lane + 64 * i] = u32x2{pk2(o4.x, o4.y), pk2(o4.z, o4.w)};
.LBB0_1487:
	s_and_b64 vcc, exec, s[58:59]
	s_cbranch_vccz .LBB0_2495
	v_readlane_b32 s10, v255, 21
	v_readlane_b32 s11, v255, 22
	s_mov_b64 s[8:9], -1
	s_and_b64 vcc, exec, s[10:11]
	s_cbranch_vccz .LBB0_1503
	s_mov_b64 s[12:13], exec
	v_readlane_b32 s8, v255, 15
	v_readlane_b32 s9, v255, 16
	s_nop 0
	s_load_dwordx4 s[16:19], s[8:9], 0x20
	s_load_dwordx4 s[20:23], s[8:9], 0xf0
	v_readlane_b32 s2, v255, 13
	v_and_b32_e32 v2, 63, v182
	v_lshrrev_b32_e32 v3, 6, v182
	v_lshlrev_b32_e32 v4, 5, v2
	v_lshlrev_b32_e32 v5, 4, v2
	s_lshl_b32 s10, s2, 12
	s_cmp_eq_u32 s2, 3
	s_cselect_b32 s14, 1, 0
	v_readfirstlane_b32 s15, v3
	s_lshl_b32 s11, s94, 3
	s_waitcnt lgkmcnt(0)
	s_add_u32 s16, s16, s10
	s_addc_u32 s17, s17, 0
	s_add_u32 s18, s18, s10
	s_addc_u32 s19, s19, 0
	global_load_dwordx4 v[8:11], v4, s[16:17]
	global_load_dwordx4 v[24:27], v4, s[18:19]
	global_load_dwordx4 v[12:15], v4, s[16:17] offset:16
	global_load_dwordx4 v[28:31], v4, s[18:19] offset:16
	global_load_dwordx4 v[16:19], v4, s[16:17] offset:2048
	global_load_dwordx4 v[32:35], v4, s[18:19] offset:2048
	global_load_dwordx4 v[20:23], v4, s[16:17] offset:2064
	global_load_dwordx4 v[36:39], v4, s[18:19] offset:2064
	s_add_u32 s11, s11, s15
	s_lshl_b32 s15, s96, 3
	s_add_u32 s8, s22, 0x3000000
	s_addc_u32 s9, s23, 0
	s_add_u32 s22, s22, 0x1d980000
	s_addc_u32 s23, s23, 0
	s_cmpk_ge_u32 s11, 0x8000
	s_cbranch_scc1 .Llnb_done
	s_lshl_b32 s2, s11, 12
	s_add_u32 s16, s20, s2
	s_addc_u32 s17, s21, 0
	s_lshl_b32 s10, s15, 12
	s_add_u32 s18, s16, s10
	s_addc_u32 s19, s17, 0
	global_load_dwordx4 v[40:43], v4, s[16:17]
	global_load_dwordx4 v[44:47], v4, s[16:17] offset:16
	global_load_dwordx4 v[48:51], v4, s[16:17] offset:2048
	global_load_dwordx4 v[52:55], v4, s[16:17] offset:2064
	global_load_dwordx4 v[56:59], v4, s[18:19]
	global_load_dwordx4 v[60:63], v4, s[18:19] offset:16
	global_load_dwordx4 v[64:67], v4, s[18:19] offset:2048
	global_load_dwordx4 v[68:71], v4, s[18:19] offset:2064
	s_lshl_b32 s10, s15, 1
	s_add_u32 s10, s11, s10
	s_cmpk_lt_u32 s10, 0x8000
	s_cselect_b32 s10, s10, s11
	s_lshl_b32 s2, s10, 12
	s_add_u32 s16, s20, s2
	s_addc_u32 s17, s21, 0
	s_lshl_b32 s10, s15, 12
	s_add_u32 s18, s16, s10
	s_addc_u32 s19, s17, 0
	global_load_dwordx4 v[72:75], v4, s[16:17]
	global_load_dwordx4 v[76:79], v4, s[16:17] offset:16
	global_load_dwordx4 v[80:83], v4, s[16:17] offset:2048
	global_load_dwordx4 v[84:87], v4, s[16:17] offset:2064
	global_load_dwordx4 v[88:91], v4, s[18:19]
	global_load_dwordx4 v[92:95], v4, s[18:19] offset:16
	global_load_dwordx4 v[96:99], v4, s[18:19] offset:2048
	global_load_dwordx4 v[100:103], v4, s[18:19] offset:2064
	s_waitcnt vmcnt(8)
	v_add_f32_e32 v104, v40, v41
	v_add_f32_e32 v105, v56, v57
	v_add_f32_e32 v104, v104, v42
	v_add_f32_e32 v105, v105, v58
	v_add_f32_e32 v104, v104, v43
	v_add_f32_e32 v105, v105, v59
	v_add_f32_e32 v104, v104, v44
	v_add_f32_e32 v105, v105, v60
	v_add_f32_e32 v104, v104, v45
	v_add_f32_e32 v105, v105, v61
	v_add_f32_e32 v104, v104, v46
	v_add_f32_e32 v105, v105, v62
	v_add_f32_e32 v104, v104, v47
	v_add_f32_e32 v105, v105, v63
	v_add_f32_e32 v104, v104, v48
	v_add_f32_e32 v105, v105, v64
	v_add_f32_e32 v104, v104, v49
	v_add_f32_e32 v105, v105, v65
	v_add_f32_e32 v104, v104, v50
	v_add_f32_e32 v105, v105, v66
	v_add_f32_e32 v104, v104, v51
	v_add_f32_e32 v105, v105, v67
	v_add_f32_e32 v104, v104, v52
	v_add_f32_e32 v105, v105, v68
	v_add_f32_e32 v104, v104, v53
	v_add_f32_e32 v105, v105, v69
	v_add_f32_e32 v104, v104, v54
	v_add_f32_e32 v105, v105, v70
	v_add_f32_e32 v104, v104, v55
	v_add_f32_e32 v105, v105, v71
	s_nop 1
	v_add_f32_dpp v104, v104, v104 quad_perm:[1,0,3,2] row_mask:0xf bank_mask:0xf
	v_add_f32_dpp v105, v105, v105 quad_perm:[1,0,3,2] row_mask:0xf bank_mask:0xf
	s_nop 1
	v_add_f32_dpp v104, v104, v104 quad_perm:[2,3,0,1] row_mask:0xf bank_mask:0xf
	v_add_f32_dpp v105, v105, v105 quad_perm:[2,3,0,1] row_mask:0xf bank_mask:0xf
	s_nop 1
	v_add_f32_dpp v104, v104, v104 row_half_mirror row_mask:0xf bank_mask:0xf
	v_add_f32_dpp v105, v105, v105 row_half_mirror row_mask:0xf bank_mask:0xf
	s_nop 1
	v_add_f32_dpp v104, v104, v104 row_mirror row_mask:0xf bank_mask:0xf
	v_add_f32_dpp v105, v105, v105 row_mirror row_mask:0xf bank_mask:0xf
	s_nop 1
	v_readlane_b32 s2, v104, 0
	v_readlane_b32 s10, v104, 16
	v_readlane_b32 s16, v104, 32
	v_readlane_b32 s17, v104, 48
	v_readlane_b32 s18, v105, 0
	v_readlane_b32 s19, v105, 16
	v_mov_b32_e32 v104, s2
	v_add_f32_e32 v104, s10, v104
	v_add_f32_e32 v104, s16, v104
	v_add_f32_e32 v104, s17, v104
	v_readlane_b32 s2, v105, 32
	v_readlane_b32 s10, v105, 48
	v_mov_b32_e32 v105, s18
	v_add_f32_e32 v105, s19, v105
	s_nop 0
	v_add_f32_e32 v105, s2, v105
	v_add_f32_e32 v105, s10, v105
	v_mul_f32_e32 v108, 0x3a800000, v104
	v_mul_f32_e32 v110, 0x3a800000, v105
	v_sub_f32_e32 v40, v40, v108
	v_sub_f32_e32 v56, v56, v110
	v_sub_f32_e32 v41, v41, v108
	v_sub_f32_e32 v57, v57, v110
	v_sub_f32_e32 v42, v42, v108
	v_sub_f32_e32 v58, v58, v110
	v_sub_f32_e32 v43, v43, v108
	v_sub_f32_e32 v59, v59, v110
	v_sub_f32_e32 v44, v44, v108
	v_sub_f32_e32 v60, v60, v110
	v_sub_f32_e32 v45, v45, v108
	v_sub_f32_e32 v61, v61, v110
	v_sub_f32_e32 v46, v46, v108
	v_sub_f32_e32 v62, v62, v110
	v_sub_f32_e32 v47, v47, v108
	v_sub_f32_e32 v63, v63, v110
	v_sub_f32_e32 v48, v48, v108
; __device__ __forceinline__ void ln_phase(const PRef& P, const float* __restrict__ gw, const float* __restrict__ bw, bool write_f32) {
;     ...
;     for (int i = 0; i < 4; ++i) { s0 += v[0][i].x + v[0][i].y + v[0][i].z + v[0][i].w; s1 += v[1][i].x + v[1][i].y + v[1][i].z + v[1][i].w; }
; #pragma unroll
;     for (int o = 32; o > 0; o >>= 1) { s0 += __shfl_xor(s0, o); s1 += __shfl_xor(s1, o); }
;     const float mu0 = s0 * (1.f / DM), mu1 = s1 * (1.f / DM); float q0 = 0.f, q1 = 0.f;
; #pragma unroll
;     for (int i = 0; i < 4; ++i) { float a = v[0][i].x - mu0, b = v[0][i].y - mu0, c = v[0][i].z - mu0, d = v[0][i].w - mu0; q0 += a * a + b * b + c * c + d * d;
;       float e = v[1][i].x - mu1, f = v[1][i].y - mu1, g = v[1][i].z - mu1, h = v[1][i].w - mu1; q1 += e * e + f * f + g * g + h * h; }
; #pragma unroll
;     for (int o = 32; o > 0; o >>= 1) { q0 += __shfl_xor(q0, o); q1 += __shfl_xor(q1, o); }
;     const float rs0 = rsqrtf(q0 * (1.f / DM) + 1e-5f), rs1 = rsqrtf(q1 * (1.f / DM) + 1e-5f);
;     if (lane == 0) { st[row] = make_float2(mu0, rs0); st[row + nw] = make_float2(mu1, rs1); }
; #pragma unroll
;     for (int i = 0; i < 4; ++i) { float4 g4 = ((const float4*)gw)[lane + 64 * i], b4 = ((const float4*)bw)[lane + 64 * i]; float4 o4, p4;
;       o4.x = (v[0][i].x - mu0) * rs0 * g4.x + b4.x; o4.y = (v[0][i].y - mu0) * rs0 * g4.y + b4.y; o4.z = (v[0][i].z - mu0) * rs0 * g4.z + b4.z; o4.w = (v[0][i].w - mu0) * rs0 * g4.w + b4.w;
;       p4.x = (v[1][i].x - mu1) * rs1 * g4.x + b4.x; p4.y = (v[1][i].y - mu1) * rs1 * g4.y + b4.y; p4.z = (v[1][i].z - mu1) * rs1 * g4.z + b4.z; p4.w = (v[1][i].w - mu1) * rs1 * g4.w + b4.w;
;       if (write_f32) { hp0[lane + 64 * i] = o4; hp1[lane + 64 * i] = p4; }
	v_sub_f32_e32 v64, v64, v110
	v_sub_f32_e32 v49, v49, v108
	v_sub_f32_e32 v65, v65, v110
	v_sub_f32_e32 v50, v50, v108
	v_sub_f32_e32 v66, v66, v110
	v_sub_f32_e32 v51, v51, v108
	v_sub_f32_e32 v67, v67, v110
	v_sub_f32_e32 v52, v52, v108
	v_sub_f32_e32 v68, v68, v110
	v_sub_f32_e32 v53, v53, v108
	v_sub_f32_e32 v69, v69, v110
	v_sub_f32_e32 v54, v54, v108
	v_sub_f32_e32 v70, v70, v110
	v_sub_f32_e32 v55, v55, v108
	v_sub_f32_e32 v71, v71, v110
	v_mul_f32_e32 v106, v40, v40
	v_mul_f32_e32 v107, v56, v56
	v_fmac_f32_e32 v106, v41, v41
	v_fmac_f32_e32 v107, v57, v57
	v_fmac_f32_e32 v106, v42, v42
	v_fmac_f32_e32 v107, v58, v58
	v_fmac_f32_e32 v106, v43, v43
	v_fmac_f32_e32 v107, v59, v59
	v_fmac_f32_e32 v106, v44, v44
	v_fmac_f32_e32 v107, v60, v60
	v_fmac_f32_e32 v106, v45, v45
	v_fmac_f32_e32 v107, v61, v61
	v_fmac_f32_e32 v106, v46, v46
	v_fmac_f32_e32 v107, v62, v62
	v_fmac_f32_e32 v106, v47, v47
	v_fmac_f32_e32 v107, v63, v63
	v_fmac_f32_e32 v106, v48, v48
	v_fmac_f32_e32 v107, v64, v64
	v_fmac_f32_e32 v106, v49, v49
	v_fmac_f32_e32 v107, v65, v65
	v_fmac_f32_e32 v106, v50, v50
	v_fmac_f32_e32 v107, v66, v66
	v_fmac_f32_e32 v106, v51, v51
	v_fmac_f32_e32 v107, v67, v67
	v_fmac_f32_e32 v106, v52, v52
	v_fmac_f32_e32 v107, v68, v68
	v_fmac_f32_e32 v106, v53, v53
	v_fmac_f32_e32 v107, v69, v69
	v_fmac_f32_e32 v106, v54, v54
	v_fmac_f32_e32 v107, v70, v70
	v_fmac_f32_e32 v106, v55, v55
	v_fmac_f32_e32 v107, v71, v71
	s_nop 1
	v_add_f32_dpp v106, v106, v106 quad_perm:[1,0,3,2] row_mask:0xf bank_mask:0xf
	v_add_f32_dpp v107, v107, v107 quad_perm:[1,0,3,2] row_mask:0xf bank_mask:0xf
	s_nop 1
	v_add_f32_dpp v106, v106, v106 quad_perm:[2,3,0,1] row_mask:0xf bank_mask:0xf
	v_add_f32_dpp v107, v107, v107 quad_perm:[2,3,0,1] row_mask:0xf bank_mask:0xf
	s_nop 1
	v_add_f32_dpp v106, v106, v106 row_half_mirror row_mask:0xf bank_mask:0xf
	v_add_f32_dpp v107, v107, v107 row_half_mirror row_mask:0xf bank_mask:0xf
	s_nop 1
	v_add_f32_dpp v106, v106, v106 row_mirror row_mask:0xf bank_mask:0xf
	v_add_f32_dpp v107, v107, v107 row_mirror row_mask:0xf bank_mask:0xf
	s_nop 1
	v_readlane_b32 s2, v106, 0
	v_readlane_b32 s10, v106, 16
	v_readlane_b32 s16, v106, 32
	v_readlane_b32 s17, v106, 48
	v_readlane_b32 s18, v107, 0
	v_readlane_b32 s19, v107, 16
	v_mov_b32_e32 v106, s2
	v_add_f32_e32 v106, s10, v106
	v_add_f32_e32 v106, s16, v106
	v_add_f32_e32 v106, s17, v106
	v_readlane_b32 s2, v107, 32
	v_readlane_b32 s10, v107, 48
	v_mov_b32_e32 v107, s18
	v_add_f32_e32 v107, s19, v107
	s_nop 0
	v_add_f32_e32 v107, s2, v107
	v_add_f32_e32 v107, s10, v107
	v_mul_f32_e32 v106, 0x3a800000, v106
	v_mul_f32_e32 v107, 0x3a800000, v107
	v_add_f32_e32 v106, 0x3727c5ac, v106
	v_add_f32_e32 v107, 0x3727c5ac, v107
	v_rsq_f32_e32 v109, v106
	v_rsq_f32_e32 v111, v107
	s_nop 0
	v_mul_f32_e32 v40, v40, v109
	v_mul_f32_e32 v56, v56, v111
	v_mul_f32_e32 v41, v41, v109
	v_mul_f32_e32 v57, v57, v111
	v_mul_f32_e32 v42, v42, v109
	v_mul_f32_e32 v58, v58, v111
	v_mul_f32_e32 v43, v43, v109
	v_mul_f32_e32 v59, v59, v111
	v_mul_f32_e32 v44, v44, v109
	v_mul_f32_e32 v60, v60, v111
	v_mul_f32_e32 v45, v45, v109
	v_mul_f32_e32 v61, v61, v111
	v_mul_f32_e32 v46, v46, v109
	v_mul_f32_e32 v62, v62, v111
	v_mul_f32_e32 v47, v47, v109
	v_mul_f32_e32 v63, v63, v111
	v_mul_f32_e32 v48, v48, v109
	v_mul_f32_e32 v64, v64, v111
	v_mul_f32_e32 v49, v49, v109
	v_mul_f32_e32 v65, v65, v111
	v_mul_f32_e32 v50, v50, v109
	v_mul_f32_e32 v66, v66, v111
	v_mul_f32_e32 v51, v51, v109
	v_mul_f32_e32 v67, v67, v111
	v_mul_f32_e32 v52, v52, v109
	v_mul_f32_e32 v68, v68, v111
	v_mul_f32_e32 v53, v53, v109
	v_mul_f32_e32 v69, v69, v111
	v_mul_f32_e32 v54, v54, v109
	v_mul_f32_e32 v70, v70, v111
	v_mul_f32_e32 v55, v55, v109
	v_mul_f32_e32 v71, v71, v111
	v_fma_f32 v40, v40, v8, v24
	v_fma_f32 v56, v56, v8, v24
	v_fma_f32 v41, v41, v9, v25
	v_fma_f32 v57, v57, v9, v25
	v_fma_f32 v42, v42, v10, v26
	v_fma_f32 v58, v58, v10, v26
	v_fma_f32 v43, v43, v11, v27
	v_fma_f32 v59, v59, v11, v27
	v_fma_f32 v44, v44, v12, v28
	v_fma_f32 v60, v60, v12, v28
	v_fma_f32 v45, v45, v13, v29
	v_fma_f32 v61, v61, v13, v29
	v_fma_f32 v46, v46, v14, v30
	v_fma_f32 v62, v62, v14, v30
	v_fma_f32 v47, v47, v15, v31
	v_fma_f32 v63, v63, v15, v31
	v_fma_f32 v48, v48, v16, v32
	v_fma_f32 v64, v64, v16, v32
	v_fma_f32 v49, v49, v17, v33
	v_fma_f32 v65, v65, v17, v33
	v_fma_f32 v50, v50, v18, v34
	v_fma_f32 v66, v66, v18, v34
	v_fma_f32 v51, v51, v19, v35
	v_fma_f32 v67, v67, v19, v35
	v_fma_f32 v52, v52, v20, v36
	v_fma_f32 v68, v68, v20, v36
	v_fma_f32 v53, v53, v21, v37
	v_fma_f32 v69, v69, v21, v37
	v_fma_f32 v54, v54, v22, v38
	v_fma_f32 v70, v70, v22, v38
	v_fma_f32 v55, v55, v23, v39
	v_fma_f32 v71, v71, v23, v39
	s_lshl_b32 s2, s11, 12
	s_add_u32 s16, s20, s2
	s_addc_u32 s17, s21, 0
	s_lshl_b32 s10, s15, 12
	s_add_u32 s18, s16, s10
	s_addc_u32 s19, s17, 0
	s_cmp_eq_u32 s14, 0
	s_cbranch_scc1 .Llnb_nof32_p0
	global_store_dwordx4 v4, v[40:43], s[16:17]
	global_store_dwordx4 v4, v[44:47], s[16:17] offset:16
	global_store_dwordx4 v4, v[48:51], s[16:17] offset:2048
	global_store_dwordx4 v4, v[52:55], s[16:17] offset:2064
	global_store_dwordx4 v4, v[56:59], s[18:19]
	global_store_dwordx4 v4, v[60:63], s[18:19] offset:16
	global_store_dwordx4 v4, v[64:67], s[18:19] offset:2048
	global_store_dwordx4 v4, v[68:71], s[18:19] offset:2064
